# P3 kv-up items: second k-slice's LDS-DMA loads issued together with the first slice's, before the first wait
# baseline (speedup 1.0000x reference)
; DI void wait_vm0() { asm volatile("s_waitcnt vmcnt(0)" ::: "memory"); }
; DI void bar_() { __builtin_amdgcn_s_barrier(); }
; #define GLDS(gp, lp) __builtin_amdgcn_global_load_lds((const unsigned*)(gp), (__attribute__((address_space(3))) unsigned*)(lp), 16, 0, 0)
; #define SB_ __builtin_amdgcn_sched_barrier(0)
; #define LOADF(A_, B_, ks) do { const int po_ = (((ks) * 2 + hh) ^ sw) * 16; \
;       _Pragma("unroll") for (int tm = 0; tm < TM; ++tm) A_[tm] = *(const bf16x8*)(As + tm * 32 * LDR + po_); \
;       _Pragma("unroll") for (int tn = 0; tn < TN; ++tn) B_[tn] = *(const bf16x8*)(Bs + tn * 32 * LDR + po_); } while (0)
; template <int TM, int TN, int WM, int WN, bool SUMSQ, int NST, class AF, class BF, class AFN, class BFN>
; DI void gemm8x(f32x16 (&acc)[TM][TN], AF arow, BF brow, int K, char* smem, float& sumsq, bool pre, bool hasNext, AFN arowN, BFN browN) {
;     ...
;   if (!pre) {
;     char* l_ = smem + t * 16; char* m_ = l_ + RA * LDR;
;     if (a0v) GLDS(pa0, l_); if (a1v) GLDS(pa1, l_ + 8192); if (a2v) GLDS(pa2, l_ + 16384); if (a3v) GLDS(pa3, l_ + 24576);
;     if (b0v) GLDS(pb0, m_); if (b1v) GLDS(pb1, m_ + 8192); if (b2v) GLDS(pb2, m_ + 16384); if (b3v) GLDS(pb3, m_ + 24576);
;   }
;   if (NST == 3) {
;     char* l_ = smem + STAGE + t * 16; char* m_ = l_ + RA * LDR;
;     GLDS(pa0 + 64, l_); GLDS(pa1 + 64, l_ + 8192); GLDS(pa2 + 64, l_ + 16384); GLDS(pa3 + 64, l_ + 24576);
;     GLDS(pb0 + 64, m_); GLDS(pb1 + 64, m_ + 8192);
;     asm volatile("s_waitcnt vmcnt(6)" ::: "memory");
;   } else wait_vm0();
;   bar_();
;     ...
;     if (issue) { if (a0v) GLDS(q0, l_); if (a1v) GLDS(q1, l_ + 8192); }
;     SB_;
;     __builtin_amdgcn_s_setprio(1);
;     MMF(a0, b0);
;     LOADF(a0, b0, 2);
;     SB_;
;     if (issue) { if (a2v) GLDS(q2, l_ + 16384); if (a3v) GLDS(q3, l_ + 24576); }
;     SB_;
;     MMF(a1, b1);
;     LOADF(a1, b1, 3);
;     SB_;
;     if (issue) { if (b0v) GLDS(s0, m_); if (b1v) GLDS(s1, m_ + 8192); }
;     SB_;
;     MMF(a0, b0);
;     SB_;
;     if (issue) { if (b2v) GLDS(s2, m_ + 16384); if (b3v) GLDS(s3, m_ + 24576); }
.LBB0_474:
	s_or_b64 exec, exec, s[58:59]
	v_add_u32_e32 v143, 0xc000, v116
	v_add_u32_e32 v144, 0xe000, v116
	v_add_u32_e32 v168, 0x10000, v116
	v_add_u32_e32 v169, 0x12000, v116
	v_add_u32_e32 v170, 0x14000, v116
	v_add_u32_e32 v172, 0x16000, v116
	s_nop 0
	s_and_saveexec_b64 s[58:59], vcc
	s_cbranch_execz .LBB0_476
	v_readfirstlane_b32 s60, v143
	v_lshl_add_u64 v[16:17], v[136:137], 0, s[44:45]
	s_mov_b32 m0, s60
	s_nop 0
	global_load_lds_dwordx4 v[16:17], off
.LBB0_476:
	s_or_b64 exec, exec, s[58:59]
	s_and_saveexec_b64 s[58:59], s[4:5]
	s_cbranch_execz .LBB0_478
	v_readfirstlane_b32 s60, v144
	v_lshl_add_u64 v[16:17], v[138:139], 0, s[44:45]
	s_mov_b32 m0, s60
	s_nop 0
	global_load_lds_dwordx4 v[16:17], off
.LBB0_478:
	s_or_b64 exec, exec, s[58:59]
	s_and_saveexec_b64 s[58:59], s[6:7]
	s_cbranch_execz .LBB0_480
	v_readfirstlane_b32 s60, v168
	v_lshl_add_u64 v[110:111], v[148:149], 0, s[44:45]
	s_mov_b32 m0, s60
	s_nop 0
	global_load_lds_dwordx4 v[110:111], off
.LBB0_480:
	s_or_b64 exec, exec, s[58:59]
	s_and_saveexec_b64 s[58:59], s[10:11]
	s_cbranch_execz .LBB0_482
	v_readfirstlane_b32 s60, v169
	v_lshl_add_u64 v[110:111], v[156:157], 0, s[44:45]
	s_mov_b32 m0, s60
	s_nop 0
	global_load_lds_dwordx4 v[110:111], off
.LBB0_482:
	s_or_b64 exec, exec, s[58:59]
	s_and_saveexec_b64 s[58:59], s[8:9]
	s_cbranch_execz .LBB0_484
	v_readfirstlane_b32 s60, v168
	v_lshl_add_u64 v[80:81], v[150:151], 0, s[44:45]
	s_mov_b32 m0, s60
	s_nop 0
	global_load_lds_dwordx4 v[80:81], off

; DI void wait_vm0() { asm volatile("s_waitcnt vmcnt(0)" ::: "memory"); }
; DI void bar_() { __builtin_amdgcn_s_barrier(); }
; #define GLDS(gp, lp) __builtin_amdgcn_global_load_lds((const unsigned*)(gp), (__attribute__((address_space(3))) unsigned*)(lp), 16, 0, 0)
; #define SB_ __builtin_amdgcn_sched_barrier(0)
; template <int TM, int TN, int WM, int WN, bool SUMSQ, int NST, class AF, class BF, class AFN, class BFN>
; DI void gemm8x(f32x16 (&acc)[TM][TN], AF arow, BF brow, int K, char* smem, float& sumsq, bool pre, bool hasNext, AFN arowN, BFN browN) {
;     ...
;   } else wait_vm0();
;   bar_();
;   const int nk = K >> 6;
;   const int sw = (r >> 1) & 7;
;   const int aoff = (wm * TM * 32 + r) * LDR, boff = RA * LDR + (wn * TN * 32 + r) * LDR;
;   auto compute = [&](const char* cur, char* nxt, bool issue, const bf16_t* q0, const bf16_t* q1, const bf16_t* q2, const bf16_t* q3,
;                      const bf16_t* s0, const bf16_t* s1, const bf16_t* s2, const bf16_t* s3) {
;     const char* As = cur + aoff;
;     const char* Bs = cur + boff;
;     char* l_ = nxt + t * 16; char* m_ = l_ + RA * LDR;
;     bf16x8 a0[TM], b0[TN], a1[TM], b1[TN];
;     ...
;     LOADF(a0, b0, 0);
;     LOADF(a1, b1, 1);
;     SB_;
;     if (issue) { if (a0v) GLDS(q0, l_); if (a1v) GLDS(q1, l_ + 8192); }
;     SB_;
;     __builtin_amdgcn_s_setprio(1);
;     MMF(a0, b0);
;     LOADF(a0, b0, 2);
;     SB_;
;     if (issue) { if (a2v) GLDS(q2, l_ + 16384); if (a3v) GLDS(q3, l_ + 24576); }
;     SB_;
;     MMF(a1, b1);
;     LOADF(a1, b1, 3);
;     SB_;
;     if (issue) { if (b0v) GLDS(s0, m_); if (b1v) GLDS(s1, m_ + 8192); }
;     SB_;
;     MMF(a0, b0);
;     SB_;
;     if (issue) { if (b2v) GLDS(s2, m_ + 16384); if (b3v) GLDS(s3, m_ + 24576); }
;     SB_;
;     MMF(a1, b1);
;     __builtin_amdgcn_s_setprio(0);
;   };
;   int sc_ = 0;
;   for (int kt = 0; kt < nk - 1; ++kt) {
;     SB_;
;     if (NST == 2) {
;       const int ko = (kt + 1) * 64;
;       compute(smem + (kt & 1) * STAGE, smem + ((kt + 1) & 1) * STAGE, true, pa0 + ko, pa1 + ko, pa2 + ko, pa3 + ko, pb0 + ko, pb1 + ko, pb2 + ko, pb3 + ko);
;       SB_;
;       wait_vm0(); bar_();
.LBB0_486:
	s_or_b64 exec, exec, s[58:59]
	s_and_saveexec_b64 s[58:59], vcc
	s_cbranch_execz .LBB0_488
	v_readfirstlane_b32 s60, v170
	v_lshl_add_u64 v[80:81], v[152:153], 0, s[44:45]
	s_mov_b32 m0, s60
	s_nop 0
	global_load_lds_dwordx4 v[80:81], off
.LBB0_488:
	s_or_b64 exec, exec, s[58:59]
	s_and_saveexec_b64 s[58:59], s[4:5]
	s_cbranch_execz .LBB0_490
	v_readfirstlane_b32 s60, v172
	v_lshl_add_u64 v[80:81], v[158:159], 0, s[44:45]
	s_mov_b32 m0, s60
	s_nop 0
	global_load_lds_dwordx4 v[80:81], off
.LBB0_490:
	s_or_b64 exec, exec, s[58:59]
	v_and_b32_e32 v1, 31, v0
	v_lshrrev_b32_e32 v2, 1, v0
	v_bfe_u32 v108, v0, 5, 1
	v_bfe_u32 v109, v0, 1, 3
	v_and_or_b32 v0, v2, s83, v1
	s_waitcnt vmcnt(0)
	v_lshlrev_b32_e32 v140, 7, v0
	v_bitop3_b32 v0, v2, v108, 7 bitop3:0x6c
	v_lshlrev_b32_e32 v142, 4, v0
	v_bitop3_b32 v0, v108, v109, 2 bitop3:0x36
	v_lshlrev_b32_e32 v118, 7, v1
	v_lshlrev_b32_e32 v141, 4, v0
	s_barrier
	v_or_b32_e32 v0, v118, v142
	v_or_b32_e32 v16, v140, v142
	ds_read_b128 v[4:7], v0
	ds_read_b128 v[8:11], v0 offset:4096
	ds_read_b128 v[12:15], v0 offset:8192
	ds_read_b128 v[0:3], v0 offset:12288
	v_or_b32_e32 v17, v118, v141
	ds_read_b128 v[68:71], v16 offset:16384
	ds_read_b128 v[92:95], v17
	ds_read_b128 v[84:87], v17 offset:4096
	ds_read_b128 v[76:79], v17 offset:8192
	v_or_b32_e32 v16, v140, v141
	ds_read_b128 v[80:83], v17 offset:12288
	ds_read_b128 v[64:67], v16 offset:16384
	v_add_u32_e32 v143, 0xc000, v116
	v_add_u32_e32 v144, 0xe000, v116
	v_bitop3_b32 v16, v108, v109, 4 bitop3:0x36
	v_lshlrev_b32_e32 v128, 4, v16
	v_add_u32_e32 v168, 0x10000, v116
	s_setprio 1
	s_waitcnt lgkmcnt(0)
	v_mfma_f32_32x32x16_bf16 v[48:63], v[4:7], v[68:71], 0
	v_add_u32_e32 v161, v118, v128
	ds_read_b128 v[104:107], v161
	ds_read_b128 v[100:103], v161 offset:4096
	ds_read_b128 v[96:99], v161 offset:8192
	ds_read_b128 v[88:91], v161 offset:12288
	v_add_u32_e32 v171, v140, v128
	ds_read_b128 v[72:75], v171 offset:16384
	v_mfma_f32_32x32x16_bf16 v[32:47], v[8:11], v[68:71], 0
	v_mfma_f32_32x32x16_bf16 v[16:31], v[12:15], v[68:71], 0
	v_mfma_f32_32x32x16_bf16 v[0:15], v[0:3], v[68:71], 0
	v_add_u32_e32 v169, 0x12000, v116
	v_bitop3_b32 v108, v108, v109, 6 bitop3:0x36
	v_lshlrev_b32_e32 v145, 4, v108
	v_mfma_f32_32x32x16_bf16 v[48:63], v[92:95], v[64:67], v[48:63]
	v_add_u32_e32 v160, v118, v145
	v_add_u32_e32 v173, v140, v145
	v_mfma_f32_32x32x16_bf16 v[32:47], v[84:87], v[64:67], v[32:47]
	ds_read_b128 v[112:115], v160
	ds_read_b128 v[108:111], v160 offset:4096
	ds_read_b128 v[92:95], v160 offset:8192
	ds_read_b128 v[84:87], v160 offset:12288
	v_mfma_f32_32x32x16_bf16 v[16:31], v[76:79], v[64:67], v[16:31]
	ds_read_b128 v[76:79], v173 offset:16384
	v_mfma_f32_32x32x16_bf16 v[0:15], v[80:83], v[64:67], v[0:15]
	s_waitcnt lgkmcnt(0)
	v_mfma_f32_32x32x16_bf16 v[48:63], v[104:107], v[72:75], v[48:63]
	v_mfma_f32_32x32x16_bf16 v[32:47], v[100:103], v[72:75], v[32:47]
	v_mfma_f32_32x32x16_bf16 v[16:31], v[96:99], v[72:75], v[16:31]
	v_mfma_f32_32x32x16_bf16 v[0:15], v[88:91], v[72:75], v[0:15]
	v_add_u32_e32 v170, 0x14000, v116
	v_add_u32_e32 v172, 0x16000, v116
	v_mfma_f32_32x32x16_bf16 v[48:63], v[112:115], v[76:79], v[48:63]
	v_mfma_f32_32x32x16_bf16 v[32:47], v[108:111], v[76:79], v[32:47]
	v_mfma_f32_32x32x16_bf16 v[16:31], v[92:95], v[76:79], v[16:31]
	v_mfma_f32_32x32x16_bf16 v[0:15], v[84:87], v[76:79], v[0:15]
	s_setprio 0
	s_waitcnt vmcnt(0)
	s_barrier
	v_or_b32_e32 v80, 0xc000, v142
	v_add_u32_e32 v162, v118, v142
	v_add_u32_e32 v165, v80, v140
	ds_read_b128 v[108:111], v162 offset:49152
	ds_read_b128 v[100:103], v162 offset:53248
	ds_read_b128 v[88:91], v162 offset:57344
	ds_read_b128 v[124:127], v162 offset:61440
	v_add_u32_e32 v163, v118, v141
	ds_read_b128 v[84:87], v165 offset:16384
	ds_read_b128 v[112:115], v163 offset:49152
	ds_read_b128 v[104:107], v163 offset:53248
	ds_read_b128 v[92:95], v163 offset:57344
	v_or_b32_e32 v80, 0xc000, v141
	v_add_u32_e32 v166, v80, v140
	ds_read_b128 v[96:99], v163 offset:61440
	ds_read_b128 v[80:83], v166 offset:16384
	s_and_saveexec_b64 s[58:59], vcc
	s_cbranch_execz .LBB0_492
	v_readfirstlane_b32 s60, v116
	v_lshl_add_u64 v[118:119], v[136:137], 0, s[46:47]
	s_mov_b32 m0, s60
	s_nop 0
	global_load_lds_dwordx4 v[118:119], off
